# P8: waves without an own A^T tile skip the A phase; a duplicate second tile is not recomputed
# speedup vs baseline: 1.0403x; 1.0042x over previous
.Lp8_lat_0:
	s_cmp_eq_u32 s37, 0
	s_cbranch_scc0 .Lp8_lat1_0
	s_sub_i32 s48, 3, s12
	s_sub_i32 s49, 39, s12
	s_cmp_lt_u32 s12, 4
	s_cselect_b32 s48, s48, s49
	s_cmp_eq_u32 s31, 0
	s_cselect_b32 s54, s12, s48
	s_lshl_b32 s48, s54, 6
	s_add_i32 s49, s33, s48
	s_add_i32 s48, s34, s48
	s_cmp_lt_u32 s54, 4
	s_cselect_b32 s55, s49, s48
	s_add_i32 s48, s55, 0
	s_add_i32 s49, s55, 48
	s_cmp_eq_u32 s31, 0
	s_cselect_b32 s48, s48, s49
	s_lshl_b32 s48, s48, 11
	s_add_u32 s8, s28, s48
	s_addc_u32 s9, s29, 0
	s_add_i32 s48, s55, 48
	s_add_i32 s49, s55, 0
	s_cmp_eq_u32 s31, 0
	s_cselect_b32 s48, s48, s49
	s_lshl_b32 s48, s48, 11
	s_add_u32 s10, s28, s48
	s_addc_u32 s11, s29, 0
	v_cvt_pk_bf16_f32 v150, v2, v3
	v_cvt_pk_bf16_f32 v151, v4, v5
	v_cvt_pk_bf16_f32 v152, v6, v7
	v_cvt_pk_bf16_f32 v153, v8, v9
	v_cvt_pk_bf16_f32 v154, v10, v11
	v_cvt_pk_bf16_f32 v155, v12, v13
	v_cvt_pk_bf16_f32 v156, v14, v15
	v_cvt_pk_bf16_f32 v157, v16, v17
	v_cvt_pk_bf16_f32 v158, v18, v19
	v_cvt_pk_bf16_f32 v159, v20, v21
	v_cvt_pk_bf16_f32 v160, v22, v23
	v_cvt_pk_bf16_f32 v161, v24, v25
	v_cvt_pk_bf16_f32 v162, v26, v27
	v_cvt_pk_bf16_f32 v163, v28, v29
	v_cvt_pk_bf16_f32 v164, v30, v31
	v_cvt_pk_bf16_f32 v165, v32, v33
	ds_read_b64_tr_b16 v[126:127], v184 offset:35840
	ds_read_b64_tr_b16 v[128:129], v184 offset:38400
	ds_read_b64_tr_b16 v[130:131], v184 offset:40960
	ds_read_b64_tr_b16 v[132:133], v184 offset:43520
	ds_read_b64_tr_b16 v[62:63], v185 offset:17408
	ds_read_b64_tr_b16 v[64:65], v185 offset:22016
	ds_read_b64_tr_b16 v[66:67], v185 offset:26624
	ds_read_b64_tr_b16 v[68:69], v185 offset:31232
	ds_read_b64_tr_b16 v[70:71], v185 offset:17440
	ds_read_b64_tr_b16 v[72:73], v185 offset:22048
	ds_read_b64_tr_b16 v[74:75], v185 offset:26656
	ds_read_b64_tr_b16 v[76:77], v185 offset:31264
	ds_read_b64_tr_b16 v[78:79], v185 offset:17472
	ds_read_b64_tr_b16 v[80:81], v185 offset:22080
	ds_read_b64_tr_b16 v[82:83], v185 offset:26688
	ds_read_b64_tr_b16 v[84:85], v185 offset:31296
	ds_read_b64_tr_b16 v[86:87], v185 offset:17504
	ds_read_b64_tr_b16 v[88:89], v185 offset:22112
	ds_read_b64_tr_b16 v[90:91], v185 offset:26720
	ds_read_b64_tr_b16 v[92:93], v185 offset:31328
	ds_read_b64 v[94:95], v183 offset:0
	ds_read_b64 v[96:97], v183 offset:32
	ds_read_b64 v[98:99], v183 offset:64
	ds_read_b64 v[100:101], v183 offset:96
	ds_read_b64 v[102:103], v183 offset:128
	ds_read_b64 v[104:105], v183 offset:160
	ds_read_b64 v[106:107], v183 offset:192
	ds_read_b64 v[108:109], v183 offset:224
	ds_read_b64 v[110:111], v183 offset:13056
	ds_read_b64 v[112:113], v183 offset:13088
	ds_read_b64 v[114:115], v183 offset:13120
	ds_read_b64 v[116:117], v183 offset:13152
	ds_read_b64 v[118:119], v183 offset:13184
	ds_read_b64 v[120:121], v183 offset:13216
	ds_read_b64 v[122:123], v183 offset:13248
	ds_read_b64 v[124:125], v183 offset:13280
	s_waitcnt lgkmcnt(15)
	v_mfma_f32_16x16x32_bf16 v[2:5], v[62:65], v[126:129], v[2:5]
	v_mfma_f32_16x16x32_bf16 v[2:5], v[66:69], v[130:133], v[2:5]
	v_mfma_f32_16x16x32_bf16 v[6:9], v[70:73], v[126:129], v[6:9]
	v_mfma_f32_16x16x32_bf16 v[6:9], v[74:77], v[130:133], v[6:9]
	v_mfma_f32_16x16x32_bf16 v[10:13], v[78:81], v[126:129], v[10:13]
	v_mfma_f32_16x16x32_bf16 v[10:13], v[82:85], v[130:133], v[10:13]
	v_mfma_f32_16x16x32_bf16 v[14:17], v[86:89], v[126:129], v[14:17]
	v_mfma_f32_16x16x32_bf16 v[14:17], v[90:93], v[130:133], v[14:17]
	s_waitcnt lgkmcnt(0)
	v_mfma_f32_16x16x32_bf16 v[34:37], v[150:153], v[94:97], 0
	v_mfma_f32_16x16x32_bf16 v[38:41], v[150:153], v[110:113], 0
	v_mfma_f32_16x16x32_bf16 v[34:37], v[154:157], v[98:101], v[34:37]
	v_mfma_f32_16x16x32_bf16 v[38:41], v[154:157], v[114:117], v[38:41]
	v_mfma_f32_16x16x32_bf16 v[34:37], v[158:161], v[102:105], v[34:37]
	v_mfma_f32_16x16x32_bf16 v[38:41], v[158:161], v[118:121], v[38:41]
	v_mfma_f32_16x16x32_bf16 v[34:37], v[162:165], v[106:109], v[34:37]
	v_mfma_f32_16x16x32_bf16 v[38:41], v[162:165], v[122:125], v[38:41]
	s_nop 7
	s_barrier
	s_cmp_eq_u32 s36, 3
	s_cbranch_scc1 .Lp8_noa_2
	ds_read_b128 v[62:65], v56 offset:0
	ds_read_b128 v[66:69], v56 offset:64
	ds_read_b128 v[70:73], v56 offset:128
	ds_read_b128 v[74:77], v56 offset:192
	ds_read_b128 v[166:169], v54 offset:17408
	ds_read_b128 v[170:173], v54 offset:17472
	ds_read_b128 v[174:177], v54 offset:17536
	ds_read_b128 v[178:181], v54 offset:17600
	s_cmp_eq_u32 s98, s99
	s_cbranch_scc1 .Lp8_nokb_3
	ds_read_b128 v[200:203], v55 offset:17408
	ds_read_b128 v[204:207], v55 offset:17472
	ds_read_b128 v[208:211], v55 offset:17536
	ds_read_b128 v[212:215], v55 offset:17600
.Lp8_nokb_3:
.Lp8_noa_2:
	s_cmp_gt_u32 s12, 5
	s_cbranch_scc1 .Lp8_w10_4
	s_waitcnt vmcnt(6)
	s_branch .Lp8_wd_4

.Lp8_wd_4:
	ds_write_b128 v243, v[142:145] offset:17408
	ds_write_b128 v243, v[146:149] offset:26624
	ds_write_b128 v190, v[238:241] offset:35840
	ds_write_b128 v189, v[134:137]
	ds_write_b128 v189, v[138:141] offset:8704
	ds_write_b32 v191, v237
	s_add_i32 s64, s12, 3
	s_min_u32 s65, s64, 35
	s_sub_i32 s48, 3, s65
	s_sub_i32 s49, 39, s65
	s_cmp_lt_u32 s65, 4
	s_cselect_b32 s48, s48, s49
	s_cmp_eq_u32 s31, 0
	s_cselect_b32 s54, s65, s48
	s_lshl_b32 s48, s54, 6
	s_add_i32 s49, s33, s48
	s_add_i32 s48, s34, s48
	s_cmp_lt_u32 s54, 4
	s_cselect_b32 s55, s49, s48
	s_mul_i32 s48, s55, s30
	s_add_u32 s0, s16, s48
	s_addc_u32 s1, s17, 0
	s_add_u32 s2, s18, s48
	s_addc_u32 s3, s19, 0
	s_mul_i32 s48, s55, 0x1800
	s_add_u32 s4, s20, s48
	s_addc_u32 s5, s21, 0
	s_lshl_b32 s48, s54, 9
	s_add_u32 s6, s22, s48
	s_addc_u32 s7, s23, 0
	global_load_dwordx4 v[142:145], v244, s[2:3]
	global_load_dwordx4 v[146:149], v245, s[2:3]
	global_load_dwordx4 v[238:241], v246, s[4:5]
	global_load_dwordx4 v[134:137], v244, s[0:1]
	global_load_dwordx4 v[138:141], v245, s[0:1]
	global_load_dword v237, v194, s[6:7]
	s_cmp_eq_u32 s36, 3
	s_cbranch_scc1 .Lp8_noat_5
	s_waitcnt lgkmcnt(6)
	v_mfma_f32_16x16x32_bf16 v[42:45], v[166:169], v[62:65], 0
	v_mfma_f32_16x16x32_bf16 v[42:45], v[170:173], v[66:69], v[42:45]
	v_mfma_f32_16x16x32_bf16 v[42:45], v[174:177], v[70:73], v[42:45]
	v_mfma_f32_16x16x32_bf16 v[42:45], v[178:181], v[74:77], v[42:45]
	s_cmp_eq_u32 s98, s99
	s_nop 6
	s_cbranch_scc1 .Lp8_nob1_6
	v_mfma_f32_16x16x32_bf16 v[46:49], v[200:203], v[62:65], 0
	v_mfma_f32_16x16x32_bf16 v[46:49], v[204:207], v[66:69], v[46:49]
	v_mfma_f32_16x16x32_bf16 v[46:49], v[208:211], v[70:73], v[46:49]
	v_mfma_f32_16x16x32_bf16 v[46:49], v[212:215], v[74:77], v[46:49]
	s_nop 7
.Lp8_nob1_6:
	v_cndmask_b32_e64 v42, v42, 0, s[40:41]
	v_cndmask_b32_e64 v43, v43, 0, s[42:43]
	v_cndmask_b32_e64 v44, v44, 0, s[44:45]
	v_cndmask_b32_e64 v45, v45, 0, s[46:47]
	v_cvt_pk_bf16_f32 v50, v42, v43
	v_cvt_pk_bf16_f32 v51, v44, v45
	ds_write_b64 v57, v[50:51]
	s_cmp_eq_u32 s98, s99
	s_cbranch_scc1 .Lp8_nob2_6
	v_cndmask_b32_e64 v46, v46, 0, s[80:81]
	v_cndmask_b32_e64 v47, v47, 0, s[82:83]
	v_cndmask_b32_e64 v48, v48, 0, s[84:85]
	v_cndmask_b32_e64 v49, v49, 0, s[86:87]
	v_cvt_pk_bf16_f32 v52, v46, v47
	v_cvt_pk_bf16_f32 v53, v48, v49
	ds_write_b64 v58, v[52:53]
	s_nop 0
.Lp8_nob2_6:
.Lp8_noat_5:
	s_waitcnt lgkmcnt(0)
	s_barrier
	ds_read_b64_tr_b16 v[62:63], v185 offset:17536
	ds_read_b64_tr_b16 v[64:65], v185 offset:22144
	ds_read_b64_tr_b16 v[66:67], v185 offset:26752
	ds_read_b64_tr_b16 v[68:69], v185 offset:31360
	ds_read_b64_tr_b16 v[70:71], v185 offset:17568
	ds_read_b64_tr_b16 v[72:73], v185 offset:22176
	ds_read_b64_tr_b16 v[74:75], v185 offset:26784
	ds_read_b64_tr_b16 v[76:77], v185 offset:31392
	ds_read_b64_tr_b16 v[78:79], v185 offset:17600
	ds_read_b64_tr_b16 v[80:81], v185 offset:22208
	ds_read_b64_tr_b16 v[82:83], v185 offset:26816
	ds_read_b64_tr_b16 v[84:85], v185 offset:31424
	ds_read_b64_tr_b16 v[86:87], v185 offset:17632
	ds_read_b64_tr_b16 v[88:89], v185 offset:22240
	ds_read_b64_tr_b16 v[90:91], v185 offset:26848
	ds_read_b64_tr_b16 v[92:93], v185 offset:31456
	ds_read_b128 v[150:153], v59 offset:0
	ds_read_b128 v[154:157], v59 offset:7680
	ds_read_b128 v[158:161], v59 offset:7744
	ds_read_b128 v[166:169], v188 offset:0
	ds_read_b128 v[170:173], v188 offset:64
	ds_read_b128 v[174:177], v188 offset:128
	ds_read_b128 v[178:181], v188 offset:192
	ds_read_b128 v[200:203], v188 offset:256
	ds_read_b128 v[204:207], v188 offset:320
	ds_read_b128 v[208:211], v188 offset:384
	ds_read_b128 v[212:215], v188 offset:448
	s_waitcnt lgkmcnt(11)
	v_mfma_f32_16x16x32_bf16 v[18:21], v[62:65], v[126:129], v[18:21]
	v_mfma_f32_16x16x32_bf16 v[18:21], v[66:69], v[130:133], v[18:21]
	v_mfma_f32_16x16x32_bf16 v[22:25], v[70:73], v[126:129], v[22:25]
	v_mfma_f32_16x16x32_bf16 v[22:25], v[74:77], v[130:133], v[22:25]
	v_mfma_f32_16x16x32_bf16 v[26:29], v[78:81], v[126:129], v[26:29]
	v_mfma_f32_16x16x32_bf16 v[26:29], v[82:85], v[130:133], v[26:29]
	v_mfma_f32_16x16x32_bf16 v[30:33], v[86:89], v[126:129], v[30:33]
	v_mfma_f32_16x16x32_bf16 v[30:33], v[90:93], v[130:133], v[30:33]
	s_waitcnt lgkmcnt(8)
	v_mfma_f32_16x16x32_bf16 v[34:37], v[126:129], v[150:153], v[34:37]
	v_mfma_f32_16x16x32_bf16 v[38:41], v[126:129], v[154:157], v[38:41]
	v_mfma_f32_16x16x32_bf16 v[38:41], v[130:133], v[158:161], v[38:41]
	s_waitcnt lgkmcnt(0)
	v_pk_mul_f32 v[2:3], v[2:3], v[166:167]
	v_pk_mul_f32 v[4:5], v[4:5], v[168:169]
	v_pk_mul_f32 v[6:7], v[6:7], v[170:171]
	v_pk_mul_f32 v[8:9], v[8:9], v[172:173]
	v_pk_mul_f32 v[10:11], v[10:11], v[174:175]
	v_pk_mul_f32 v[12:13], v[12:13], v[176:177]
	v_pk_mul_f32 v[14:15], v[14:15], v[178:179]
	v_pk_mul_f32 v[16:17], v[16:17], v[180:181]
	v_pk_mul_f32 v[18:19], v[18:19], v[200:201]
	v_pk_mul_f32 v[20:21], v[20:21], v[202:203]
	v_pk_mul_f32 v[22:23], v[22:23], v[204:205]
	v_pk_mul_f32 v[24:25], v[24:25], v[206:207]
	v_pk_mul_f32 v[26:27], v[26:27], v[208:209]
	v_pk_mul_f32 v[28:29], v[28:29], v[210:211]
	v_pk_mul_f32 v[30:31], v[30:31], v[212:213]
	v_pk_mul_f32 v[32:33], v[32:33], v[214:215]
	v_cvt_pk_bf16_f32 v50, v34, v35
	v_cvt_pk_bf16_f32 v51, v36, v37
	global_store_dwordx2 v247, v[50:51], s[8:9]
	v_cvt_pk_bf16_f32 v52, v38, v39
	v_cvt_pk_bf16_f32 v53, v40, v41
	global_store_dwordx2 v247, v[52:53], s[10:11]
	s_nop 0
	s_barrier
	s_branch .Lp8_next_0

.Lp8_first_7:
	s_sub_i32 s48, 3, s12
	s_sub_i32 s49, 39, s12
	s_cmp_lt_u32 s12, 4
	s_cselect_b32 s48, s48, s49
	s_cmp_eq_u32 s31, 0
	s_cselect_b32 s54, s12, s48
	s_lshl_b32 s48, s54, 6
	s_add_i32 s49, s33, s48
	s_add_i32 s48, s34, s48
	s_cmp_lt_u32 s54, 4
	s_cselect_b32 s55, s49, s48
	s_add_i32 s48, s55, 16
	s_add_i32 s49, s55, 32
	s_cmp_eq_u32 s31, 0
	s_cselect_b32 s48, s48, s49
	s_lshl_b32 s48, s48, 11
	s_add_u32 s8, s28, s48
	s_addc_u32 s9, s29, 0
	s_add_i32 s48, s55, 32
	s_add_i32 s49, s55, 16
	s_cmp_eq_u32 s31, 0
	s_cselect_b32 s48, s48, s49
	s_lshl_b32 s48, s48, 11
	s_add_u32 s10, s28, s48
	s_addc_u32 s11, s29, 0
	v_cvt_pk_bf16_f32 v150, v2, v3
	v_cvt_pk_bf16_f32 v151, v4, v5
	v_cvt_pk_bf16_f32 v152, v6, v7
	v_cvt_pk_bf16_f32 v153, v8, v9
	v_cvt_pk_bf16_f32 v154, v10, v11
	v_cvt_pk_bf16_f32 v155, v12, v13
	v_cvt_pk_bf16_f32 v156, v14, v15
	v_cvt_pk_bf16_f32 v157, v16, v17
	v_cvt_pk_bf16_f32 v158, v18, v19
	v_cvt_pk_bf16_f32 v159, v20, v21
	v_cvt_pk_bf16_f32 v160, v22, v23
	v_cvt_pk_bf16_f32 v161, v24, v25
	v_cvt_pk_bf16_f32 v162, v26, v27
	v_cvt_pk_bf16_f32 v163, v28, v29
	v_cvt_pk_bf16_f32 v164, v30, v31
	v_cvt_pk_bf16_f32 v165, v32, v33
	ds_read_b64_tr_b16 v[126:127], v184 offset:35840
	ds_read_b64_tr_b16 v[128:129], v184 offset:38400
	ds_read_b64_tr_b16 v[130:131], v184 offset:40960
	ds_read_b64_tr_b16 v[132:133], v184 offset:43520
	ds_read_b64_tr_b16 v[62:63], v185 offset:17408
	ds_read_b64_tr_b16 v[64:65], v185 offset:22016
	ds_read_b64_tr_b16 v[66:67], v185 offset:26624
	ds_read_b64_tr_b16 v[68:69], v185 offset:31232
	ds_read_b64_tr_b16 v[70:71], v185 offset:17440
	ds_read_b64_tr_b16 v[72:73], v185 offset:22048
	ds_read_b64_tr_b16 v[74:75], v185 offset:26656
	ds_read_b64_tr_b16 v[76:77], v185 offset:31264
	ds_read_b64_tr_b16 v[78:79], v185 offset:17472
	ds_read_b64_tr_b16 v[80:81], v185 offset:22080
	ds_read_b64_tr_b16 v[82:83], v185 offset:26688
	ds_read_b64_tr_b16 v[84:85], v185 offset:31296
	ds_read_b64_tr_b16 v[86:87], v185 offset:17504
	ds_read_b64_tr_b16 v[88:89], v185 offset:22112
	ds_read_b64_tr_b16 v[90:91], v185 offset:26720
	ds_read_b64_tr_b16 v[92:93], v185 offset:31328
	ds_read_b64 v[94:95], v183 offset:4352
	ds_read_b64 v[96:97], v183 offset:4384
	ds_read_b64 v[98:99], v183 offset:4416
	ds_read_b64 v[100:101], v183 offset:4448
	ds_read_b64 v[102:103], v183 offset:4480
	ds_read_b64 v[104:105], v183 offset:4512
	ds_read_b64 v[106:107], v183 offset:4544
	ds_read_b64 v[108:109], v183 offset:4576
	ds_read_b64 v[110:111], v183 offset:8704
	ds_read_b64 v[112:113], v183 offset:8736
	ds_read_b64 v[114:115], v183 offset:8768
	ds_read_b64 v[116:117], v183 offset:8800
	ds_read_b64 v[118:119], v183 offset:8832
	ds_read_b64 v[120:121], v183 offset:8864
	ds_read_b64 v[122:123], v183 offset:8896
	ds_read_b64 v[124:125], v183 offset:8928
	s_barrier
	s_waitcnt lgkmcnt(15)
	v_mfma_f32_16x16x32_bf16 v[2:5], v[62:65], v[126:129], v[2:5]
	v_mfma_f32_16x16x32_bf16 v[2:5], v[66:69], v[130:133], v[2:5]
	v_mfma_f32_16x16x32_bf16 v[6:9], v[70:73], v[126:129], v[6:9]
	v_mfma_f32_16x16x32_bf16 v[6:9], v[74:77], v[130:133], v[6:9]
	v_mfma_f32_16x16x32_bf16 v[10:13], v[78:81], v[126:129], v[10:13]
	v_mfma_f32_16x16x32_bf16 v[10:13], v[82:85], v[130:133], v[10:13]
	v_mfma_f32_16x16x32_bf16 v[14:17], v[86:89], v[126:129], v[14:17]
	v_mfma_f32_16x16x32_bf16 v[14:17], v[90:93], v[130:133], v[14:17]
	s_waitcnt lgkmcnt(0)
	v_mfma_f32_16x16x32_bf16 v[34:37], v[150:153], v[94:97], 0
	v_mfma_f32_16x16x32_bf16 v[38:41], v[150:153], v[110:113], 0
	v_mfma_f32_16x16x32_bf16 v[34:37], v[154:157], v[98:101], v[34:37]
	v_mfma_f32_16x16x32_bf16 v[38:41], v[154:157], v[114:117], v[38:41]
	v_mfma_f32_16x16x32_bf16 v[34:37], v[158:161], v[102:105], v[34:37]
	v_mfma_f32_16x16x32_bf16 v[38:41], v[158:161], v[118:121], v[38:41]
	v_mfma_f32_16x16x32_bf16 v[34:37], v[162:165], v[106:109], v[34:37]
	v_mfma_f32_16x16x32_bf16 v[38:41], v[162:165], v[122:125], v[38:41]
	s_cmp_eq_u32 s36, 3
	s_nop 6
	s_cbranch_scc1 .Lp8_noa_8
	ds_read_b128 v[62:65], v56 offset:0
	ds_read_b128 v[66:69], v56 offset:64
	ds_read_b128 v[70:73], v56 offset:128
	ds_read_b128 v[74:77], v56 offset:192
	ds_read_b128 v[166:169], v54 offset:17408
	ds_read_b128 v[170:173], v54 offset:17472
	ds_read_b128 v[174:177], v54 offset:17536
	ds_read_b128 v[178:181], v54 offset:17600
	s_cmp_eq_u32 s98, s99
	s_cbranch_scc1 .Lp8_nokb_9
	ds_read_b128 v[200:203], v55 offset:17408
	ds_read_b128 v[204:207], v55 offset:17472
	ds_read_b128 v[208:211], v55 offset:17536
	ds_read_b128 v[212:215], v55 offset:17600

.Lp8_wd_10:
	ds_write_b128 v243, v[142:145] offset:17408
	ds_write_b128 v243, v[146:149] offset:26624
	ds_write_b128 v190, v[238:241] offset:35840
	ds_write_b128 v189, v[134:137]
	ds_write_b128 v189, v[138:141] offset:8704
	ds_write_b32 v191, v237
	s_add_i32 s64, s12, 3
	s_min_u32 s65, s64, 35
	s_sub_i32 s48, 3, s65
	s_sub_i32 s49, 39, s65
	s_cmp_lt_u32 s65, 4
	s_cselect_b32 s48, s48, s49
	s_cmp_eq_u32 s31, 0
	s_cselect_b32 s54, s65, s48
	s_lshl_b32 s48, s54, 6
	s_add_i32 s49, s33, s48
	s_add_i32 s48, s34, s48
	s_cmp_lt_u32 s54, 4
	s_cselect_b32 s55, s49, s48
	s_mul_i32 s48, s55, s30
	s_add_u32 s0, s16, s48
	s_addc_u32 s1, s17, 0
	s_add_u32 s2, s18, s48
	s_addc_u32 s3, s19, 0
	s_mul_i32 s48, s55, 0x1800
	s_add_u32 s4, s20, s48
	s_addc_u32 s5, s21, 0
	s_lshl_b32 s48, s54, 9
	s_add_u32 s6, s22, s48
	s_addc_u32 s7, s23, 0
	global_load_dwordx4 v[142:145], v244, s[2:3]
	global_load_dwordx4 v[146:149], v245, s[2:3]
	global_load_dwordx4 v[238:241], v246, s[4:5]
	global_load_dwordx4 v[134:137], v244, s[0:1]
	global_load_dwordx4 v[138:141], v245, s[0:1]
	global_load_dword v237, v194, s[6:7]
	s_barrier
	s_cmp_eq_u32 s36, 3
	s_cbranch_scc1 .Lp8_noat_11
	s_waitcnt lgkmcnt(6)
	v_mfma_f32_16x16x32_bf16 v[42:45], v[166:169], v[62:65], 0
	v_mfma_f32_16x16x32_bf16 v[42:45], v[170:173], v[66:69], v[42:45]
	v_mfma_f32_16x16x32_bf16 v[42:45], v[174:177], v[70:73], v[42:45]
	v_mfma_f32_16x16x32_bf16 v[42:45], v[178:181], v[74:77], v[42:45]
	s_cmp_eq_u32 s98, s99
	s_nop 6
	s_cbranch_scc1 .Lp8_nob1_12
	v_mfma_f32_16x16x32_bf16 v[46:49], v[200:203], v[62:65], 0
	v_mfma_f32_16x16x32_bf16 v[46:49], v[204:207], v[66:69], v[46:49]
	v_mfma_f32_16x16x32_bf16 v[46:49], v[208:211], v[70:73], v[46:49]
	v_mfma_f32_16x16x32_bf16 v[46:49], v[212:215], v[74:77], v[46:49]
	s_nop 7

.Lp8_nob2_12:
.Lp8_noat_11:
	ds_read_b64_tr_b16 v[62:63], v185 offset:17536
	ds_read_b64_tr_b16 v[64:65], v185 offset:22144
	ds_read_b64_tr_b16 v[66:67], v185 offset:26752
	ds_read_b64_tr_b16 v[68:69], v185 offset:31360
	ds_read_b64_tr_b16 v[70:71], v185 offset:17568
	ds_read_b64_tr_b16 v[72:73], v185 offset:22176
	ds_read_b64_tr_b16 v[74:75], v185 offset:26784
	ds_read_b64_tr_b16 v[76:77], v185 offset:31392
	ds_read_b64_tr_b16 v[78:79], v185 offset:17600
	ds_read_b64_tr_b16 v[80:81], v185 offset:22208
	ds_read_b64_tr_b16 v[82:83], v185 offset:26816
	ds_read_b64_tr_b16 v[84:85], v185 offset:31424
	ds_read_b64_tr_b16 v[86:87], v185 offset:17632
	ds_read_b64_tr_b16 v[88:89], v185 offset:22240
	ds_read_b64_tr_b16 v[90:91], v185 offset:26848
	ds_read_b64_tr_b16 v[92:93], v185 offset:31456
	ds_read_b128 v[166:169], v188 offset:0
	ds_read_b128 v[170:173], v188 offset:64
	ds_read_b128 v[174:177], v188 offset:128
	ds_read_b128 v[178:181], v188 offset:192
	ds_read_b128 v[200:203], v188 offset:256
	ds_read_b128 v[204:207], v188 offset:320
	ds_read_b128 v[208:211], v188 offset:384
	ds_read_b128 v[212:215], v188 offset:448
	s_mov_b64 s[76:77], s[8:9]
	s_mov_b64 s[78:79], s[10:11]
	s_waitcnt lgkmcnt(15)
	s_barrier

.Lp8_wd_16:
	ds_write_b128 v243, v[224:227] offset:17408
	ds_write_b128 v243, v[228:231] offset:26624
	ds_write_b128 v190, v[232:235] offset:35840
	ds_write_b128 v189, v[216:219]
	ds_write_b128 v189, v[220:223] offset:8704
	ds_write_b32 v191, v236
	s_add_i32 s64, s12, 3
	s_min_u32 s65, s64, 35
	s_sub_i32 s48, 3, s65
	s_sub_i32 s49, 39, s65
	s_cmp_lt_u32 s65, 4
	s_cselect_b32 s48, s48, s49
	s_cmp_eq_u32 s31, 0
	s_cselect_b32 s54, s65, s48
	s_lshl_b32 s48, s54, 6
	s_add_i32 s49, s33, s48
	s_add_i32 s48, s34, s48
	s_cmp_lt_u32 s54, 4
	s_cselect_b32 s55, s49, s48
	s_mul_i32 s48, s55, s30
	s_add_u32 s0, s16, s48
	s_addc_u32 s1, s17, 0
	s_add_u32 s2, s18, s48
	s_addc_u32 s3, s19, 0
	s_mul_i32 s48, s55, 0x1800
	s_add_u32 s4, s20, s48
	s_addc_u32 s5, s21, 0
	s_lshl_b32 s48, s54, 9
	s_add_u32 s6, s22, s48
	s_addc_u32 s7, s23, 0
	global_load_dwordx4 v[224:227], v244, s[2:3]
	global_load_dwordx4 v[228:231], v245, s[2:3]
	global_load_dwordx4 v[232:235], v246, s[4:5]
	global_load_dwordx4 v[216:219], v244, s[0:1]
	global_load_dwordx4 v[220:223], v245, s[0:1]
	global_load_dword v236, v194, s[6:7]
	s_cmp_eq_u32 s36, 3
	s_cbranch_scc1 .Lp8_noat_17
	s_waitcnt lgkmcnt(6)
	v_mfma_f32_16x16x32_bf16 v[42:45], v[166:169], v[62:65], 0
	v_mfma_f32_16x16x32_bf16 v[42:45], v[170:173], v[66:69], v[42:45]
	v_mfma_f32_16x16x32_bf16 v[42:45], v[174:177], v[70:73], v[42:45]
	v_mfma_f32_16x16x32_bf16 v[42:45], v[178:181], v[74:77], v[42:45]
	s_cmp_eq_u32 s98, s99
	s_nop 6
	s_cbranch_scc1 .Lp8_nob1_18
	v_mfma_f32_16x16x32_bf16 v[46:49], v[200:203], v[62:65], 0
	v_mfma_f32_16x16x32_bf16 v[46:49], v[204:207], v[66:69], v[46:49]
	v_mfma_f32_16x16x32_bf16 v[46:49], v[208:211], v[70:73], v[46:49]
	v_mfma_f32_16x16x32_bf16 v[46:49], v[212:215], v[74:77], v[46:49]
	s_nop 7

.Lp8_wd_22:
	ds_write_b128 v243, v[224:227] offset:17408
	ds_write_b128 v243, v[228:231] offset:26624
	ds_write_b128 v190, v[232:235] offset:35840
	ds_write_b128 v189, v[216:219]
	ds_write_b128 v189, v[220:223] offset:8704
	ds_write_b32 v191, v236
	s_add_i32 s64, s12, 3
	s_min_u32 s65, s64, 35
	s_sub_i32 s48, 3, s65
	s_sub_i32 s49, 39, s65
	s_cmp_lt_u32 s65, 4
	s_cselect_b32 s48, s48, s49
	s_cmp_eq_u32 s31, 0
	s_cselect_b32 s54, s65, s48
	s_lshl_b32 s48, s54, 6
	s_add_i32 s49, s33, s48
	s_add_i32 s48, s34, s48
	s_cmp_lt_u32 s54, 4
	s_cselect_b32 s55, s49, s48
	s_mul_i32 s48, s55, s30
	s_add_u32 s0, s16, s48
	s_addc_u32 s1, s17, 0
	s_add_u32 s2, s18, s48
	s_addc_u32 s3, s19, 0
	s_mul_i32 s48, s55, 0x1800
	s_add_u32 s4, s20, s48
	s_addc_u32 s5, s21, 0
	s_lshl_b32 s48, s54, 9
	s_add_u32 s6, s22, s48
	s_addc_u32 s7, s23, 0
	global_load_dwordx4 v[224:227], v244, s[2:3]
	global_load_dwordx4 v[228:231], v245, s[2:3]
	global_load_dwordx4 v[232:235], v246, s[4:5]
	global_load_dwordx4 v[216:219], v244, s[0:1]
	global_load_dwordx4 v[220:223], v245, s[0:1]
	global_load_dword v236, v194, s[6:7]
	s_barrier
	s_cmp_eq_u32 s36, 3
	s_cbranch_scc1 .Lp8_noat_23
	s_waitcnt lgkmcnt(6)
	v_mfma_f32_16x16x32_bf16 v[42:45], v[166:169], v[62:65], 0
	v_mfma_f32_16x16x32_bf16 v[42:45], v[170:173], v[66:69], v[42:45]
	v_mfma_f32_16x16x32_bf16 v[42:45], v[174:177], v[70:73], v[42:45]
	v_mfma_f32_16x16x32_bf16 v[42:45], v[178:181], v[74:77], v[42:45]
	s_cmp_eq_u32 s98, s99
	s_nop 6
	s_cbranch_scc1 .Lp8_nob1_24
	v_mfma_f32_16x16x32_bf16 v[46:49], v[200:203], v[62:65], 0
	v_mfma_f32_16x16x32_bf16 v[46:49], v[204:207], v[66:69], v[46:49]
	v_mfma_f32_16x16x32_bf16 v[46:49], v[208:211], v[70:73], v[46:49]
	v_mfma_f32_16x16x32_bf16 v[46:49], v[212:215], v[74:77], v[46:49]
	s_nop 7
